# v098 + loop-edge edit (7.11): generic GEMM K-loop back edge rotated: pointer/counter updates, exit test and next-iteration head SALU run before the loop-back barrier; exit path has its own barrier cop
# baseline (speedup 1.0000x reference)
; #define PG8_STAGE(bufoff, gbase, voff) do { _Pragma("unroll") for (int _i = 0; _i < 2; ++_i) \
;         __builtin_amdgcn_global_load_lds((const unsigned*)((const char*)(gbase) + (voff)[_i]), (PG8_LAS unsigned*)(lds + (bufoff) + ldsw + _i * 8192), 16, 0, 0); } while (0)
; #define PG8_LDA(dst, b, h) do { _Pragma("unroll") for (int m = 0; m < 4; ++m) _Pragma("unroll") for (int k = 0; k < 2; ++k) dst[m][k] = *(const PG8_LAS bf16x8*)(lds + PG8_SA(b, h) + aoff + m * 2048 + k * 1024); } while (0)
; #define PG8_LDB(dst, b, h) do { _Pragma("unroll") for (int n = 0; n < 2; ++n) _Pragma("unroll") for (int k = 0; k < 2; ++k) dst[n][k] = *(const PG8_LAS bf16x8*)(lds + PG8_SB(b, h) + boff + n * 2048 + k * 1024); } while (0)
; template <class Epi, class Sched, bool ALIGN_EPI = false>
; __device__ __forceinline__ void gemm_phase(PG8_LAS unsigned char* lds, const Gemm g, const Sched& S, const Epi& E, int tid_in) {
;     ...
;         for (int t = 0; t < nt; t += 2) {
;             const bool last = (t == nt - 2);
;             const char* a1 = cA + (size_t)(t + 1) * kstep;
;             const char* a2 = last ? nA : cA + (size_t)(t + 2) * kstep; const char* b2 = last ? nB : cB + (size_t)(t + 2) * kstep;
;             const char* a3 = a2 + kstep; const char* b3 = b2 + kstep;
;             if (last && has_next) S.a_ready(nxt);
;             E.mid(acc, cur, t, tid_, wr, wc);
;             PG8_LDB(B0, 0, 0); PG8_LDB(B1, 0, 1); PG8_SCHED; PG8_LDA(At, 0, 0); PG8_STAGE(PG8_SA(1, 1), a1 + hstepA, voffA);
;             PG8_WAIT_V(8); PG8_WAIT_L(0); PG8_BAR; PG8_MMA(0, 0, At, B0); PG8_MMA(0, 1, At, B1); PG8_BAR; PG8_SCHED;
;             PG8_LDA(At, 0, 1); PG8_STAGE(PG8_SB(0, 0), b2, voffB); PG8_STAGE(PG8_SB(0, 1), b2 + hstepB, voffB); PG8_STAGE(PG8_SA(0, 0), a2, voffA);
;             PG8_WAIT_V(8); PG8_WAIT_L(0); PG8_BAR; PG8_MMA(1, 0, At, B0); PG8_MMA(1, 1, At, B1); PG8_BAR; PG8_SCHED;
;             PG8_LDB(B0, 1, 0); PG8_LDB(B1, 1, 1); PG8_SCHED; PG8_LDA(At, 1, 0); PG8_STAGE(PG8_SA(0, 1), a2 + hstepA, voffA);
;             PG8_WAIT_V(8); PG8_WAIT_L(0); PG8_BAR; PG8_MMA(0, 0, At, B0); PG8_MMA(0, 1, At, B1); PG8_BAR; PG8_SCHED;
;             PG8_LDA(At, 1, 1); PG8_STAGE(PG8_SB(1, 0), b3, voffB); PG8_STAGE(PG8_SB(1, 1), b3 + hstepB, voffB); PG8_STAGE(PG8_SA(1, 0), a3, voffA);
;             PG8_WAIT_V(8); PG8_WAIT_L(0); PG8_BAR; PG8_MMA(1, 0, At, B0); PG8_MMA(1, 1, At, B1); PG8_BAR; PG8_SCHED;
.LBB0_266:
	s_add_u32 s60, s60, 0x80
	s_addc_u32 s61, s61, 0
	s_add_u32 s57, s58, 0x100
	s_addc_u32 s62, s59, 0
	s_mov_b32 s58, 0
	s_cmp_eq_u32 s64, 2
	s_cbranch_scc1 .Lk_nopeel
	s_add_i32 s63, s58, 2
	s_add_u32 s22, s60, 0x80
	s_addc_u32 s23, s61, 0
	s_add_i32 s89, 0, 0x10000
	s_cmp_eq_u32 s77, s58
	s_cselect_b32 s59, s19, s23
	s_cselect_b32 s58, s18, s22
	v_add_u32_e32 v80, s89, v245
	s_cselect_b32 s23, s35, s62
	s_cselect_b32 s22, s34, s57
	s_add_i32 s90, 0, 0x14000
	ds_read_b128 v[130:133], v80
	ds_read_b128 v[134:137], v80 offset:1024
	ds_read_b128 v[138:141], v80 offset:2048
	ds_read_b128 v[142:145], v80 offset:3072
	v_add_u32_e32 v80, s90, v245
	ds_read_b128 v[146:149], v80
	ds_read_b128 v[150:153], v80 offset:1024
	ds_read_b128 v[154:157], v80 offset:2048
	ds_read_b128 v[158:161], v80 offset:3072
	s_mov_b32 m0, s74
	ds_read_b128 v[162:165], v248
	ds_read_b128 v[166:169], v248 offset:1024
	ds_read_b128 v[170:173], v248 offset:2048
	ds_read_b128 v[174:177], v248 offset:3072
	ds_read_b128 v[178:181], v248 offset:4096
	ds_read_b128 v[198:201], v248 offset:5120
	ds_read_b128 v[202:205], v248 offset:6144
	ds_read_b128 v[206:209], v248 offset:7168
	global_load_lds_dwordx4 v184, s[60:61]
	s_mov_b32 m0, s75
	s_nop 0
	global_load_lds_dwordx4 v188, s[60:61]
	s_add_i32 m0, s70, 0xc000
	s_nop 0
	global_load_lds_dwordx4 v194, s[60:61]
	s_add_i32 m0, s70, 0xe000
	s_nop 0
	global_load_lds_dwordx4 v196, s[60:61]
	s_waitcnt vmcnt(8)
	s_waitcnt lgkmcnt(0)
	v_mfma_f32_16x16x32_bf16 v[4:7], v[130:133], v[162:165], 0
	v_mfma_f32_16x16x32_bf16 v[0:3], v[138:141], v[162:165], 0
	s_barrier
	s_setprio 1
	s_waitcnt lgkmcnt(0)
	v_mfma_f32_16x16x32_bf16 v[20:23], v[130:133], v[170:173], 0
	v_mfma_f32_16x16x32_bf16 v[16:19], v[138:141], v[170:173], 0
	v_mfma_f32_16x16x32_bf16 v[36:39], v[130:133], v[178:181], 0
	v_mfma_f32_16x16x32_bf16 v[32:35], v[138:141], v[178:181], 0
	v_mfma_f32_16x16x32_bf16 v[52:55], v[130:133], v[202:205], 0
	v_mfma_f32_16x16x32_bf16 v[48:51], v[138:141], v[202:205], 0
	v_mfma_f32_16x16x32_bf16 v[4:7], v[134:137], v[166:169], v[4:7]
	v_mfma_f32_16x16x32_bf16 v[0:3], v[142:145], v[166:169], v[0:3]
	v_mfma_f32_16x16x32_bf16 v[20:23], v[134:137], v[174:177], v[20:23]
	v_mfma_f32_16x16x32_bf16 v[16:19], v[142:145], v[174:177], v[16:19]
	v_mfma_f32_16x16x32_bf16 v[36:39], v[134:137], v[198:201], v[36:39]
	v_mfma_f32_16x16x32_bf16 v[32:35], v[142:145], v[198:201], v[32:35]
	v_mfma_f32_16x16x32_bf16 v[52:55], v[134:137], v[206:209], v[52:55]
	v_mfma_f32_16x16x32_bf16 v[48:51], v[142:145], v[206:209], v[48:51]
	s_setprio 0
	s_setprio 1
	v_mfma_f32_16x16x32_bf16 v[12:15], v[146:149], v[162:165], 0
	v_mfma_f32_16x16x32_bf16 v[8:11], v[154:157], v[162:165], 0
	v_mfma_f32_16x16x32_bf16 v[28:31], v[146:149], v[170:173], 0
	v_mfma_f32_16x16x32_bf16 v[24:27], v[154:157], v[170:173], 0
	v_mfma_f32_16x16x32_bf16 v[44:47], v[146:149], v[178:181], 0
	v_mfma_f32_16x16x32_bf16 v[40:43], v[154:157], v[178:181], 0
	v_mfma_f32_16x16x32_bf16 v[60:63], v[146:149], v[202:205], 0
	v_mfma_f32_16x16x32_bf16 v[56:59], v[154:157], v[202:205], 0
	v_mfma_f32_16x16x32_bf16 v[12:15], v[150:153], v[166:169], v[12:15]
	v_mfma_f32_16x16x32_bf16 v[8:11], v[158:161], v[166:169], v[8:11]
	v_mfma_f32_16x16x32_bf16 v[28:31], v[150:153], v[174:177], v[28:31]
	v_mfma_f32_16x16x32_bf16 v[24:27], v[158:161], v[174:177], v[24:27]
	v_mfma_f32_16x16x32_bf16 v[44:47], v[150:153], v[198:201], v[44:47]
	v_mfma_f32_16x16x32_bf16 v[40:43], v[158:161], v[198:201], v[40:43]
	v_mfma_f32_16x16x32_bf16 v[60:63], v[150:153], v[206:209], v[60:63]
	v_mfma_f32_16x16x32_bf16 v[56:59], v[158:161], v[206:209], v[56:59]
	s_setprio 0
	s_barrier
	s_add_i32 s89, s89, s69
	s_mov_b64 vcc, s[22:23]
	s_mov_b32 m0, s89
	ds_read_b128 v[162:165], v248 offset:16384
	ds_read_b128 v[166:169], v248 offset:17408
	ds_read_b128 v[170:173], v248 offset:18432
	ds_read_b128 v[174:177], v248 offset:19456
	ds_read_b128 v[178:181], v248 offset:20480
	ds_read_b128 v[198:201], v248 offset:21504
	ds_read_b128 v[202:205], v248 offset:22528
	ds_read_b128 v[206:209], v248 offset:23552
	global_load_lds_dwordx4 v186, s[22:23]
	s_add_i32 m0, s89, 0x2000
	s_add_u32 s22, s22, s33
	s_addc_u32 s23, s23, 0
	s_add_i32 s89, s90, s69
	global_load_lds_dwordx4 v190, vcc
	s_mov_b32 m0, s89
	s_nop 0
	global_load_lds_dwordx4 v186, s[22:23]
	s_add_i32 m0, s89, 0x2000
	s_nop 0
	global_load_lds_dwordx4 v190, s[22:23]
	s_waitcnt vmcnt(6)
	s_waitcnt lgkmcnt(0)
	v_mfma_f32_16x16x32_bf16 v[64:67], v[130:133], v[162:165], 0
	v_mfma_f32_16x16x32_bf16 v[68:71], v[138:141], v[162:165], 0
	s_barrier
	s_setprio 1
	s_waitcnt lgkmcnt(0)
	v_mfma_f32_16x16x32_bf16 v[82:85], v[130:133], v[170:173], 0
	v_mfma_f32_16x16x32_bf16 v[86:89], v[138:141], v[170:173], 0
	v_mfma_f32_16x16x32_bf16 v[98:101], v[130:133], v[178:181], 0
	v_mfma_f32_16x16x32_bf16 v[102:105], v[138:141], v[178:181], 0
	v_mfma_f32_16x16x32_bf16 v[114:117], v[130:133], v[202:205], 0
	v_mfma_f32_16x16x32_bf16 v[118:121], v[138:141], v[202:205], 0
	v_mfma_f32_16x16x32_bf16 v[64:67], v[134:137], v[166:169], v[64:67]
	v_mfma_f32_16x16x32_bf16 v[68:71], v[142:145], v[166:169], v[68:71]
	v_mfma_f32_16x16x32_bf16 v[82:85], v[134:137], v[174:177], v[82:85]
	v_mfma_f32_16x16x32_bf16 v[86:89], v[142:145], v[174:177], v[86:89]
	v_mfma_f32_16x16x32_bf16 v[98:101], v[134:137], v[198:201], v[98:101]
	v_mfma_f32_16x16x32_bf16 v[102:105], v[142:145], v[198:201], v[102:105]
	v_mfma_f32_16x16x32_bf16 v[114:117], v[134:137], v[206:209], v[114:117]
	v_mfma_f32_16x16x32_bf16 v[118:121], v[142:145], v[206:209], v[118:121]
	s_setprio 0
	s_setprio 1
	v_mfma_f32_16x16x32_bf16 v[76:79], v[146:149], v[162:165], 0
	v_mfma_f32_16x16x32_bf16 v[72:75], v[154:157], v[162:165], 0
	v_mfma_f32_16x16x32_bf16 v[94:97], v[146:149], v[170:173], 0
	v_mfma_f32_16x16x32_bf16 v[90:93], v[154:157], v[170:173], 0
	v_mfma_f32_16x16x32_bf16 v[110:113], v[146:149], v[178:181], 0
	v_mfma_f32_16x16x32_bf16 v[106:109], v[154:157], v[178:181], 0
	v_mfma_f32_16x16x32_bf16 v[126:129], v[146:149], v[202:205], 0
	v_mfma_f32_16x16x32_bf16 v[122:125], v[154:157], v[202:205], 0
	v_mfma_f32_16x16x32_bf16 v[76:79], v[150:153], v[166:169], v[76:79]
	v_mfma_f32_16x16x32_bf16 v[72:75], v[158:161], v[166:169], v[72:75]
	v_mfma_f32_16x16x32_bf16 v[94:97], v[150:153], v[174:177], v[94:97]
	v_mfma_f32_16x16x32_bf16 v[90:93], v[158:161], v[174:177], v[90:93]
	v_mfma_f32_16x16x32_bf16 v[110:113], v[150:153], v[198:201], v[110:113]
	v_mfma_f32_16x16x32_bf16 v[106:109], v[158:161], v[198:201], v[106:109]
	v_mfma_f32_16x16x32_bf16 v[126:129], v[150:153], v[206:209], v[126:129]
	v_mfma_f32_16x16x32_bf16 v[122:125], v[158:161], v[206:209], v[122:125]
	s_setprio 0
	s_barrier
; #define PG8_STAGE(bufoff, gbase, voff) do { _Pragma("unroll") for (int _i = 0; _i < 2; ++_i) \
;         __builtin_amdgcn_global_load_lds((const unsigned*)((const char*)(gbase) + (voff)[_i]), (PG8_LAS unsigned*)(lds + (bufoff) + ldsw + _i * 8192), 16, 0, 0); } while (0)
; #define PG8_LDA(dst, b, h) do { _Pragma("unroll") for (int m = 0; m < 4; ++m) _Pragma("unroll") for (int k = 0; k < 2; ++k) dst[m][k] = *(const PG8_LAS bf16x8*)(lds + PG8_SA(b, h) + aoff + m * 2048 + k * 1024); } while (0)
; #define PG8_LDB(dst, b, h) do { _Pragma("unroll") for (int n = 0; n < 2; ++n) _Pragma("unroll") for (int k = 0; k < 2; ++k) dst[n][k] = *(const PG8_LAS bf16x8*)(lds + PG8_SB(b, h) + boff + n * 2048 + k * 1024); } while (0)
; template <class Epi, class Sched, bool ALIGN_EPI = false>
; __device__ __forceinline__ void gemm_phase(PG8_LAS unsigned char* lds, const Gemm g, const Sched& S, const Epi& E, int tid_in) {
;     ...
;         for (int t = 0; t < nt; t += 2) {
;             const bool last = (t == nt - 2);
;             const char* a1 = cA + (size_t)(t + 1) * kstep;
;             const char* a2 = last ? nA : cA + (size_t)(t + 2) * kstep; const char* b2 = last ? nB : cB + (size_t)(t + 2) * kstep;
;             const char* a3 = a2 + kstep; const char* b3 = b2 + kstep;
;             if (last && has_next) S.a_ready(nxt);
;             E.mid(acc, cur, t, tid_, wr, wc);
;             PG8_LDB(B0, 0, 0); PG8_LDB(B1, 0, 1); PG8_SCHED; PG8_LDA(At, 0, 0); PG8_STAGE(PG8_SA(1, 1), a1 + hstepA, voffA);
;             PG8_WAIT_V(8); PG8_WAIT_L(0); PG8_BAR; PG8_MMA(0, 0, At, B0); PG8_MMA(0, 1, At, B1); PG8_BAR; PG8_SCHED;
;             PG8_LDA(At, 0, 1); PG8_STAGE(PG8_SB(0, 0), b2, voffB); PG8_STAGE(PG8_SB(0, 1), b2 + hstepB, voffB); PG8_STAGE(PG8_SA(0, 0), a2, voffA);
;             PG8_WAIT_V(8); PG8_WAIT_L(0); PG8_BAR; PG8_MMA(1, 0, At, B0); PG8_MMA(1, 1, At, B1); PG8_BAR; PG8_SCHED;
;             PG8_LDB(B0, 1, 0); PG8_LDB(B1, 1, 1); PG8_SCHED; PG8_LDA(At, 1, 0); PG8_STAGE(PG8_SA(0, 1), a2 + hstepA, voffA);
;             PG8_WAIT_V(8); PG8_WAIT_L(0); PG8_BAR; PG8_MMA(0, 0, At, B0); PG8_MMA(0, 1, At, B1); PG8_BAR; PG8_SCHED;
;             PG8_LDA(At, 1, 1); PG8_STAGE(PG8_SB(1, 0), b3, voffB); PG8_STAGE(PG8_SB(1, 1), b3 + hstepB, voffB); PG8_STAGE(PG8_SA(1, 0), a3, voffA);
;             PG8_WAIT_V(8); PG8_WAIT_L(0); PG8_BAR; PG8_MMA(1, 0, At, B0); PG8_MMA(1, 1, At, B1); PG8_BAR; PG8_SCHED;
	s_add_i32 s89, 0, 0x18000
	v_add_u32_e32 v80, s89, v245
	s_add_i32 s90, 0, 0x1c000
	ds_read_b128 v[130:133], v80
	ds_read_b128 v[134:137], v80 offset:1024
	ds_read_b128 v[138:141], v80 offset:2048
	ds_read_b128 v[142:145], v80 offset:3072
	v_add_u32_e32 v80, s90, v245
	ds_read_b128 v[146:149], v80
	ds_read_b128 v[150:153], v80 offset:1024
	ds_read_b128 v[154:157], v80 offset:2048
	ds_read_b128 v[158:161], v80 offset:3072
	s_add_u32 s22, s58, s0
	s_addc_u32 s23, s59, 0
	s_mov_b32 m0, s70
	ds_read_b128 v[162:165], v248 offset:32768
	ds_read_b128 v[166:169], v248 offset:33792
	ds_read_b128 v[170:173], v248 offset:34816
	ds_read_b128 v[174:177], v248 offset:35840
	ds_read_b128 v[178:181], v248 offset:36864
	ds_read_b128 v[198:201], v248 offset:37888
	ds_read_b128 v[202:205], v248 offset:38912
	ds_read_b128 v[206:209], v248 offset:39936
	global_load_lds_dwordx4 v184, s[58:59]
	s_mov_b32 m0, s71
	s_nop 0
	global_load_lds_dwordx4 v188, s[58:59]
	s_mov_b32 m0, s72
	s_nop 0
	global_load_lds_dwordx4 v184, s[22:23]
	s_mov_b32 m0, s73
	s_nop 0
	global_load_lds_dwordx4 v188, s[22:23]
	s_waitcnt vmcnt(8)
	s_waitcnt lgkmcnt(0)
	v_mfma_f32_16x16x32_bf16 v[4:7], v[130:133], v[162:165], v[4:7]
	v_mfma_f32_16x16x32_bf16 v[0:3], v[138:141], v[162:165], v[0:3]
	s_barrier
	s_setprio 1
	s_waitcnt lgkmcnt(0)
	v_mfma_f32_16x16x32_bf16 v[20:23], v[130:133], v[170:173], v[20:23]
	v_mfma_f32_16x16x32_bf16 v[16:19], v[138:141], v[170:173], v[16:19]
	v_mfma_f32_16x16x32_bf16 v[36:39], v[130:133], v[178:181], v[36:39]
	v_mfma_f32_16x16x32_bf16 v[32:35], v[138:141], v[178:181], v[32:35]
	v_mfma_f32_16x16x32_bf16 v[52:55], v[130:133], v[202:205], v[52:55]
	v_mfma_f32_16x16x32_bf16 v[48:51], v[138:141], v[202:205], v[48:51]
	v_mfma_f32_16x16x32_bf16 v[4:7], v[134:137], v[166:169], v[4:7]
	v_mfma_f32_16x16x32_bf16 v[0:3], v[142:145], v[166:169], v[0:3]
	v_mfma_f32_16x16x32_bf16 v[20:23], v[134:137], v[174:177], v[20:23]
	v_mfma_f32_16x16x32_bf16 v[16:19], v[142:145], v[174:177], v[16:19]
	v_mfma_f32_16x16x32_bf16 v[36:39], v[134:137], v[198:201], v[36:39]
	v_mfma_f32_16x16x32_bf16 v[32:35], v[142:145], v[198:201], v[32:35]
	v_mfma_f32_16x16x32_bf16 v[52:55], v[134:137], v[206:209], v[52:55]
	v_mfma_f32_16x16x32_bf16 v[48:51], v[142:145], v[206:209], v[48:51]
	s_setprio 0
	s_setprio 1
	v_mfma_f32_16x16x32_bf16 v[12:15], v[146:149], v[162:165], v[12:15]
	v_mfma_f32_16x16x32_bf16 v[8:11], v[154:157], v[162:165], v[8:11]
	v_mfma_f32_16x16x32_bf16 v[28:31], v[146:149], v[170:173], v[28:31]
	v_mfma_f32_16x16x32_bf16 v[24:27], v[154:157], v[170:173], v[24:27]
	v_mfma_f32_16x16x32_bf16 v[44:47], v[146:149], v[178:181], v[44:47]
	v_mfma_f32_16x16x32_bf16 v[40:43], v[154:157], v[178:181], v[40:43]
	v_mfma_f32_16x16x32_bf16 v[60:63], v[146:149], v[202:205], v[60:63]
	v_mfma_f32_16x16x32_bf16 v[56:59], v[154:157], v[202:205], v[56:59]
	v_mfma_f32_16x16x32_bf16 v[12:15], v[150:153], v[166:169], v[12:15]
	v_mfma_f32_16x16x32_bf16 v[8:11], v[158:161], v[166:169], v[8:11]
	v_mfma_f32_16x16x32_bf16 v[28:31], v[150:153], v[174:177], v[28:31]
	v_mfma_f32_16x16x32_bf16 v[24:27], v[158:161], v[174:177], v[24:27]
	v_mfma_f32_16x16x32_bf16 v[44:47], v[150:153], v[198:201], v[44:47]
	v_mfma_f32_16x16x32_bf16 v[40:43], v[158:161], v[198:201], v[40:43]
	v_mfma_f32_16x16x32_bf16 v[60:63], v[150:153], v[206:209], v[60:63]
	v_mfma_f32_16x16x32_bf16 v[56:59], v[158:161], v[206:209], v[56:59]
	s_setprio 0
	s_barrier
	s_add_i32 s22, s89, s69
	s_add_u32 vcc_lo, vcc_lo, 0x80
	s_addc_u32 vcc_hi, vcc_hi, 0
	s_mov_b32 m0, s22
	ds_read_b128 v[162:165], v248 offset:49152
	ds_read_b128 v[166:169], v248 offset:50176
	ds_read_b128 v[170:173], v248 offset:51200
	ds_read_b128 v[174:177], v248 offset:52224
	ds_read_b128 v[178:181], v248 offset:53248
	ds_read_b128 v[198:201], v248 offset:54272
	ds_read_b128 v[202:205], v248 offset:55296
	ds_read_b128 v[206:209], v248 offset:56320
	global_load_lds_dwordx4 v186, vcc
	s_add_i32 m0, s22, 0x2000
	s_add_i32 s22, s90, s69
	global_load_lds_dwordx4 v190, vcc
	s_add_u32 vcc_lo, vcc_lo, s33
	s_addc_u32 vcc_hi, vcc_hi, 0
	s_mov_b32 m0, s22
	s_nop 0
	global_load_lds_dwordx4 v186, vcc
	s_add_i32 m0, s22, 0x2000
	s_nop 0
	global_load_lds_dwordx4 v190, vcc
	s_waitcnt vmcnt(6)
	s_waitcnt lgkmcnt(0)
	v_mfma_f32_16x16x32_bf16 v[64:67], v[130:133], v[162:165], v[64:67]
	v_mfma_f32_16x16x32_bf16 v[68:71], v[138:141], v[162:165], v[68:71]
	s_barrier
	s_setprio 1
	s_waitcnt lgkmcnt(0)
	v_mfma_f32_16x16x32_bf16 v[82:85], v[130:133], v[170:173], v[82:85]
	v_mfma_f32_16x16x32_bf16 v[86:89], v[138:141], v[170:173], v[86:89]
	v_mfma_f32_16x16x32_bf16 v[98:101], v[130:133], v[178:181], v[98:101]
	v_mfma_f32_16x16x32_bf16 v[102:105], v[138:141], v[178:181], v[102:105]
	v_mfma_f32_16x16x32_bf16 v[114:117], v[130:133], v[202:205], v[114:117]
	v_mfma_f32_16x16x32_bf16 v[118:121], v[138:141], v[202:205], v[118:121]
	v_mfma_f32_16x16x32_bf16 v[64:67], v[134:137], v[166:169], v[64:67]
	v_mfma_f32_16x16x32_bf16 v[68:71], v[142:145], v[166:169], v[68:71]
	v_mfma_f32_16x16x32_bf16 v[82:85], v[134:137], v[174:177], v[82:85]
	v_mfma_f32_16x16x32_bf16 v[86:89], v[142:145], v[174:177], v[86:89]
	v_mfma_f32_16x16x32_bf16 v[98:101], v[134:137], v[198:201], v[98:101]
	v_mfma_f32_16x16x32_bf16 v[102:105], v[142:145], v[198:201], v[102:105]
	v_mfma_f32_16x16x32_bf16 v[114:117], v[134:137], v[206:209], v[114:117]
	v_mfma_f32_16x16x32_bf16 v[118:121], v[142:145], v[206:209], v[118:121]
	s_setprio 0
	s_setprio 1
	v_mfma_f32_16x16x32_bf16 v[76:79], v[146:149], v[162:165], v[76:79]
	v_mfma_f32_16x16x32_bf16 v[72:75], v[154:157], v[162:165], v[72:75]
	v_mfma_f32_16x16x32_bf16 v[94:97], v[146:149], v[170:173], v[94:97]
	v_mfma_f32_16x16x32_bf16 v[90:93], v[154:157], v[170:173], v[90:93]
	v_mfma_f32_16x16x32_bf16 v[110:113], v[146:149], v[178:181], v[110:113]
	v_mfma_f32_16x16x32_bf16 v[106:109], v[154:157], v[178:181], v[106:109]
	v_mfma_f32_16x16x32_bf16 v[126:129], v[146:149], v[202:205], v[126:129]
	v_mfma_f32_16x16x32_bf16 v[122:125], v[154:157], v[202:205], v[122:125]
	v_mfma_f32_16x16x32_bf16 v[76:79], v[150:153], v[166:169], v[76:79]
	v_mfma_f32_16x16x32_bf16 v[72:75], v[158:161], v[166:169], v[72:75]
	v_mfma_f32_16x16x32_bf16 v[94:97], v[150:153], v[174:177], v[94:97]
	v_mfma_f32_16x16x32_bf16 v[90:93], v[158:161], v[174:177], v[90:93]
	v_mfma_f32_16x16x32_bf16 v[110:113], v[150:153], v[198:201], v[110:113]
	v_mfma_f32_16x16x32_bf16 v[106:109], v[158:161], v[198:201], v[106:109]
	v_mfma_f32_16x16x32_bf16 v[126:129], v[150:153], v[206:209], v[126:129]
	v_mfma_f32_16x16x32_bf16 v[122:125], v[158:161], v[206:209], v[122:125]
	s_setprio 0
	s_add_u32 s60, s60, 0x100
	s_addc_u32 s61, s61, 0
	s_add_u32 s57, s57, 0x100
	s_addc_u32 s62, s62, 0
	s_cmp_ge_u32 s63, s76
	s_mov_b32 s58, s63
	s_cbranch_scc1 .Lk_exitbar
; #define PG8_STAGE(bufoff, gbase, voff) do { _Pragma("unroll") for (int _i = 0; _i < 2; ++_i) \
;         __builtin_amdgcn_global_load_lds((const unsigned*)((const char*)(gbase) + (voff)[_i]), (PG8_LAS unsigned*)(lds + (bufoff) + ldsw + _i * 8192), 16, 0, 0); } while (0)
; #define PG8_LDA(dst, b, h) do { _Pragma("unroll") for (int m = 0; m < 4; ++m) _Pragma("unroll") for (int k = 0; k < 2; ++k) dst[m][k] = *(const PG8_LAS bf16x8*)(lds + PG8_SA(b, h) + aoff + m * 2048 + k * 1024); } while (0)
; #define PG8_LDB(dst, b, h) do { _Pragma("unroll") for (int n = 0; n < 2; ++n) _Pragma("unroll") for (int k = 0; k < 2; ++k) dst[n][k] = *(const PG8_LAS bf16x8*)(lds + PG8_SB(b, h) + boff + n * 2048 + k * 1024); } while (0)
; template <class Epi, class Sched, bool ALIGN_EPI = false>
; __device__ __forceinline__ void gemm_phase(PG8_LAS unsigned char* lds, const Gemm g, const Sched& S, const Epi& E, int tid_in) {
;     ...
;         for (int t = 0; t < nt; t += 2) {
;             const bool last = (t == nt - 2);
;             const char* a1 = cA + (size_t)(t + 1) * kstep;
;             const char* a2 = last ? nA : cA + (size_t)(t + 2) * kstep; const char* b2 = last ? nB : cB + (size_t)(t + 2) * kstep;
;             const char* a3 = a2 + kstep; const char* b3 = b2 + kstep;
;             if (last && has_next) S.a_ready(nxt);
;             E.mid(acc, cur, t, tid_, wr, wc);
;             PG8_LDB(B0, 0, 0); PG8_LDB(B1, 0, 1); PG8_SCHED; PG8_LDA(At, 0, 0); PG8_STAGE(PG8_SA(1, 1), a1 + hstepA, voffA);
;             PG8_WAIT_V(8); PG8_WAIT_L(0); PG8_BAR; PG8_MMA(0, 0, At, B0); PG8_MMA(0, 1, At, B1); PG8_BAR; PG8_SCHED;
;             PG8_LDA(At, 0, 1); PG8_STAGE(PG8_SB(0, 0), b2, voffB); PG8_STAGE(PG8_SB(0, 1), b2 + hstepB, voffB); PG8_STAGE(PG8_SA(0, 0), a2, voffA);
;             PG8_WAIT_V(8); PG8_WAIT_L(0); PG8_BAR; PG8_MMA(1, 0, At, B0); PG8_MMA(1, 1, At, B1); PG8_BAR; PG8_SCHED;
;             PG8_LDB(B0, 1, 0); PG8_LDB(B1, 1, 1); PG8_SCHED; PG8_LDA(At, 1, 0); PG8_STAGE(PG8_SA(0, 1), a2 + hstepA, voffA);
;             PG8_WAIT_V(8); PG8_WAIT_L(0); PG8_BAR; PG8_MMA(0, 0, At, B0); PG8_MMA(0, 1, At, B1); PG8_BAR; PG8_SCHED;
;             PG8_LDA(At, 1, 1); PG8_STAGE(PG8_SB(1, 0), b3, voffB); PG8_STAGE(PG8_SB(1, 1), b3 + hstepB, voffB); PG8_STAGE(PG8_SA(1, 0), a3, voffA);
;             PG8_WAIT_V(8); PG8_WAIT_L(0); PG8_BAR; PG8_MMA(1, 0, At, B0); PG8_MMA(1, 1, At, B1); PG8_BAR; PG8_SCHED;
	s_add_i32 s63, s58, 2
	s_add_u32 s22, s60, 0x80
	s_addc_u32 s23, s61, 0
	s_add_i32 s89, 0, 0x10000
	s_cmp_eq_u32 s77, s58
	s_cselect_b32 s59, s19, s23
	s_cselect_b32 s58, s18, s22
	v_add_u32_e32 v80, s89, v245
	s_cselect_b32 s23, s35, s62
	s_cselect_b32 s22, s34, s57
	s_add_i32 s90, 0, 0x14000
	s_barrier
	s_branch .LBB0_267
.Lk_nopeel:
	s_waitcnt vmcnt(0)
	s_add_i32 s63, s58, 2
	s_add_u32 s22, s60, 0x80
	s_addc_u32 s23, s61, 0
	s_add_i32 s89, 0, 0x10000
	s_cmp_eq_u32 s77, s58
	s_cselect_b32 s59, s19, s23
	s_cselect_b32 s58, s18, s22
	v_add_u32_e32 v80, s89, v245
	s_cselect_b32 s23, s35, s62
	s_cselect_b32 s22, s34, s57
	s_add_i32 s90, 0, 0x14000
.LBB0_267:
	ds_read_b128 v[130:133], v80
	ds_read_b128 v[134:137], v80 offset:1024
	ds_read_b128 v[138:141], v80 offset:2048
	ds_read_b128 v[142:145], v80 offset:3072
	v_add_u32_e32 v80, s90, v245
	ds_read_b128 v[146:149], v80
	ds_read_b128 v[150:153], v80 offset:1024
	ds_read_b128 v[154:157], v80 offset:2048
	ds_read_b128 v[158:161], v80 offset:3072
	s_mov_b32 m0, s74
	ds_read_b128 v[162:165], v248
	ds_read_b128 v[166:169], v248 offset:1024
	ds_read_b128 v[170:173], v248 offset:2048
	ds_read_b128 v[174:177], v248 offset:3072
	ds_read_b128 v[178:181], v248 offset:4096
	ds_read_b128 v[198:201], v248 offset:5120
	ds_read_b128 v[202:205], v248 offset:6144
	ds_read_b128 v[206:209], v248 offset:7168
	global_load_lds_dwordx4 v184, s[60:61]
	s_mov_b32 m0, s75
	s_nop 0
	global_load_lds_dwordx4 v188, s[60:61]
	s_add_i32 m0, s70, 0xc000
	s_nop 0
	global_load_lds_dwordx4 v194, s[60:61]
	s_add_i32 m0, s70, 0xe000
	s_nop 0
	global_load_lds_dwordx4 v196, s[60:61]
	s_waitcnt vmcnt(8)
	s_waitcnt lgkmcnt(0)
	v_mfma_f32_16x16x32_bf16 v[4:7], v[130:133], v[162:165], v[4:7]
	v_mfma_f32_16x16x32_bf16 v[0:3], v[138:141], v[162:165], v[0:3]
	s_barrier
	s_setprio 1
	s_waitcnt lgkmcnt(0)
	v_mfma_f32_16x16x32_bf16 v[20:23], v[130:133], v[170:173], v[20:23]
	v_mfma_f32_16x16x32_bf16 v[16:19], v[138:141], v[170:173], v[16:19]
	v_mfma_f32_16x16x32_bf16 v[36:39], v[130:133], v[178:181], v[36:39]
	v_mfma_f32_16x16x32_bf16 v[32:35], v[138:141], v[178:181], v[32:35]
	v_mfma_f32_16x16x32_bf16 v[52:55], v[130:133], v[202:205], v[52:55]
	v_mfma_f32_16x16x32_bf16 v[48:51], v[138:141], v[202:205], v[48:51]
	v_mfma_f32_16x16x32_bf16 v[4:7], v[134:137], v[166:169], v[4:7]
	v_mfma_f32_16x16x32_bf16 v[0:3], v[142:145], v[166:169], v[0:3]
	v_mfma_f32_16x16x32_bf16 v[20:23], v[134:137], v[174:177], v[20:23]
	v_mfma_f32_16x16x32_bf16 v[16:19], v[142:145], v[174:177], v[16:19]
	v_mfma_f32_16x16x32_bf16 v[36:39], v[134:137], v[198:201], v[36:39]
	v_mfma_f32_16x16x32_bf16 v[32:35], v[142:145], v[198:201], v[32:35]
	v_mfma_f32_16x16x32_bf16 v[52:55], v[134:137], v[206:209], v[52:55]
	v_mfma_f32_16x16x32_bf16 v[48:51], v[142:145], v[206:209], v[48:51]
	s_setprio 0
	s_setprio 1
	v_mfma_f32_16x16x32_bf16 v[12:15], v[146:149], v[162:165], v[12:15]
	v_mfma_f32_16x16x32_bf16 v[8:11], v[154:157], v[162:165], v[8:11]
	v_mfma_f32_16x16x32_bf16 v[28:31], v[146:149], v[170:173], v[28:31]
	v_mfma_f32_16x16x32_bf16 v[24:27], v[154:157], v[170:173], v[24:27]
	v_mfma_f32_16x16x32_bf16 v[44:47], v[146:149], v[178:181], v[44:47]
	v_mfma_f32_16x16x32_bf16 v[40:43], v[154:157], v[178:181], v[40:43]
	v_mfma_f32_16x16x32_bf16 v[60:63], v[146:149], v[202:205], v[60:63]
	v_mfma_f32_16x16x32_bf16 v[56:59], v[154:157], v[202:205], v[56:59]
	v_mfma_f32_16x16x32_bf16 v[12:15], v[150:153], v[166:169], v[12:15]
	v_mfma_f32_16x16x32_bf16 v[8:11], v[158:161], v[166:169], v[8:11]
	v_mfma_f32_16x16x32_bf16 v[28:31], v[150:153], v[174:177], v[28:31]
	v_mfma_f32_16x16x32_bf16 v[24:27], v[158:161], v[174:177], v[24:27]
	v_mfma_f32_16x16x32_bf16 v[44:47], v[150:153], v[198:201], v[44:47]
	v_mfma_f32_16x16x32_bf16 v[40:43], v[158:161], v[198:201], v[40:43]
	v_mfma_f32_16x16x32_bf16 v[60:63], v[150:153], v[206:209], v[60:63]
	v_mfma_f32_16x16x32_bf16 v[56:59], v[158:161], v[206:209], v[56:59]
	s_setprio 0
	s_barrier
	s_add_i32 s89, s89, s69
	s_mov_b64 vcc, s[22:23]
	s_mov_b32 m0, s89
	ds_read_b128 v[162:165], v248 offset:16384
	ds_read_b128 v[166:169], v248 offset:17408
	ds_read_b128 v[170:173], v248 offset:18432
	ds_read_b128 v[174:177], v248 offset:19456
	ds_read_b128 v[178:181], v248 offset:20480
	ds_read_b128 v[198:201], v248 offset:21504
	ds_read_b128 v[202:205], v248 offset:22528
	ds_read_b128 v[206:209], v248 offset:23552
	global_load_lds_dwordx4 v186, s[22:23]
	s_add_i32 m0, s89, 0x2000
	s_add_u32 s22, s22, s33
	s_addc_u32 s23, s23, 0
	s_add_i32 s89, s90, s69
	global_load_lds_dwordx4 v190, vcc
	s_mov_b32 m0, s89
	s_nop 0
	global_load_lds_dwordx4 v186, s[22:23]
	s_add_i32 m0, s89, 0x2000
	s_nop 0
	global_load_lds_dwordx4 v190, s[22:23]
	s_waitcnt vmcnt(6)
	s_waitcnt lgkmcnt(0)
	v_mfma_f32_16x16x32_bf16 v[64:67], v[130:133], v[162:165], v[64:67]
	v_mfma_f32_16x16x32_bf16 v[68:71], v[138:141], v[162:165], v[68:71]
	s_barrier
; #define PG8_STAGE(bufoff, gbase, voff) do { _Pragma("unroll") for (int _i = 0; _i < 2; ++_i) \
;         __builtin_amdgcn_global_load_lds((const unsigned*)((const char*)(gbase) + (voff)[_i]), (PG8_LAS unsigned*)(lds + (bufoff) + ldsw + _i * 8192), 16, 0, 0); } while (0)
; #define PG8_LDA(dst, b, h) do { _Pragma("unroll") for (int m = 0; m < 4; ++m) _Pragma("unroll") for (int k = 0; k < 2; ++k) dst[m][k] = *(const PG8_LAS bf16x8*)(lds + PG8_SA(b, h) + aoff + m * 2048 + k * 1024); } while (0)
; #define PG8_LDB(dst, b, h) do { _Pragma("unroll") for (int n = 0; n < 2; ++n) _Pragma("unroll") for (int k = 0; k < 2; ++k) dst[n][k] = *(const PG8_LAS bf16x8*)(lds + PG8_SB(b, h) + boff + n * 2048 + k * 1024); } while (0)
; template <class Epi, class Sched, bool ALIGN_EPI = false>
; __device__ __forceinline__ void gemm_phase(PG8_LAS unsigned char* lds, const Gemm g, const Sched& S, const Epi& E, int tid_in) {
;     ...
;         for (int t = 0; t < nt; t += 2) {
;             const bool last = (t == nt - 2);
;             const char* a1 = cA + (size_t)(t + 1) * kstep;
;             const char* a2 = last ? nA : cA + (size_t)(t + 2) * kstep; const char* b2 = last ? nB : cB + (size_t)(t + 2) * kstep;
;             const char* a3 = a2 + kstep; const char* b3 = b2 + kstep;
;             if (last && has_next) S.a_ready(nxt);
;             E.mid(acc, cur, t, tid_, wr, wc);
;             PG8_LDB(B0, 0, 0); PG8_LDB(B1, 0, 1); PG8_SCHED; PG8_LDA(At, 0, 0); PG8_STAGE(PG8_SA(1, 1), a1 + hstepA, voffA);
;             PG8_WAIT_V(8); PG8_WAIT_L(0); PG8_BAR; PG8_MMA(0, 0, At, B0); PG8_MMA(0, 1, At, B1); PG8_BAR; PG8_SCHED;
;             PG8_LDA(At, 0, 1); PG8_STAGE(PG8_SB(0, 0), b2, voffB); PG8_STAGE(PG8_SB(0, 1), b2 + hstepB, voffB); PG8_STAGE(PG8_SA(0, 0), a2, voffA);
;             PG8_WAIT_V(8); PG8_WAIT_L(0); PG8_BAR; PG8_MMA(1, 0, At, B0); PG8_MMA(1, 1, At, B1); PG8_BAR; PG8_SCHED;
;             PG8_LDB(B0, 1, 0); PG8_LDB(B1, 1, 1); PG8_SCHED; PG8_LDA(At, 1, 0); PG8_STAGE(PG8_SA(0, 1), a2 + hstepA, voffA);
;             PG8_WAIT_V(8); PG8_WAIT_L(0); PG8_BAR; PG8_MMA(0, 0, At, B0); PG8_MMA(0, 1, At, B1); PG8_BAR; PG8_SCHED;
;             PG8_LDA(At, 1, 1); PG8_STAGE(PG8_SB(1, 0), b3, voffB); PG8_STAGE(PG8_SB(1, 1), b3 + hstepB, voffB); PG8_STAGE(PG8_SA(1, 0), a3, voffA);
;             PG8_WAIT_V(8); PG8_WAIT_L(0); PG8_BAR; PG8_MMA(1, 0, At, B0); PG8_MMA(1, 1, At, B1); PG8_BAR; PG8_SCHED;
	s_setprio 1
	s_waitcnt lgkmcnt(0)
	v_mfma_f32_16x16x32_bf16 v[82:85], v[130:133], v[170:173], v[82:85]
	v_mfma_f32_16x16x32_bf16 v[86:89], v[138:141], v[170:173], v[86:89]
	v_mfma_f32_16x16x32_bf16 v[98:101], v[130:133], v[178:181], v[98:101]
	v_mfma_f32_16x16x32_bf16 v[102:105], v[138:141], v[178:181], v[102:105]
	v_mfma_f32_16x16x32_bf16 v[114:117], v[130:133], v[202:205], v[114:117]
	v_mfma_f32_16x16x32_bf16 v[118:121], v[138:141], v[202:205], v[118:121]
	v_mfma_f32_16x16x32_bf16 v[64:67], v[134:137], v[166:169], v[64:67]
	v_mfma_f32_16x16x32_bf16 v[68:71], v[142:145], v[166:169], v[68:71]
	v_mfma_f32_16x16x32_bf16 v[82:85], v[134:137], v[174:177], v[82:85]
	v_mfma_f32_16x16x32_bf16 v[86:89], v[142:145], v[174:177], v[86:89]
	v_mfma_f32_16x16x32_bf16 v[98:101], v[134:137], v[198:201], v[98:101]
	v_mfma_f32_16x16x32_bf16 v[102:105], v[142:145], v[198:201], v[102:105]
	v_mfma_f32_16x16x32_bf16 v[114:117], v[134:137], v[206:209], v[114:117]
	v_mfma_f32_16x16x32_bf16 v[118:121], v[142:145], v[206:209], v[118:121]
	s_setprio 0
	s_setprio 1
	v_mfma_f32_16x16x32_bf16 v[76:79], v[146:149], v[162:165], v[76:79]
	v_mfma_f32_16x16x32_bf16 v[72:75], v[154:157], v[162:165], v[72:75]
	v_mfma_f32_16x16x32_bf16 v[94:97], v[146:149], v[170:173], v[94:97]
	v_mfma_f32_16x16x32_bf16 v[90:93], v[154:157], v[170:173], v[90:93]
	v_mfma_f32_16x16x32_bf16 v[110:113], v[146:149], v[178:181], v[110:113]
	v_mfma_f32_16x16x32_bf16 v[106:109], v[154:157], v[178:181], v[106:109]
	v_mfma_f32_16x16x32_bf16 v[126:129], v[146:149], v[202:205], v[126:129]
	v_mfma_f32_16x16x32_bf16 v[122:125], v[154:157], v[202:205], v[122:125]
	v_mfma_f32_16x16x32_bf16 v[76:79], v[150:153], v[166:169], v[76:79]
	v_mfma_f32_16x16x32_bf16 v[72:75], v[158:161], v[166:169], v[72:75]
	v_mfma_f32_16x16x32_bf16 v[94:97], v[150:153], v[174:177], v[94:97]
	v_mfma_f32_16x16x32_bf16 v[90:93], v[158:161], v[174:177], v[90:93]
	v_mfma_f32_16x16x32_bf16 v[110:113], v[150:153], v[198:201], v[110:113]
	v_mfma_f32_16x16x32_bf16 v[106:109], v[158:161], v[198:201], v[106:109]
	v_mfma_f32_16x16x32_bf16 v[126:129], v[150:153], v[206:209], v[126:129]
	v_mfma_f32_16x16x32_bf16 v[122:125], v[158:161], v[206:209], v[122:125]
	s_setprio 0
	s_barrier
	s_add_i32 s89, 0, 0x18000
	v_add_u32_e32 v80, s89, v245
	s_add_i32 s90, 0, 0x1c000
	ds_read_b128 v[130:133], v80
	ds_read_b128 v[134:137], v80 offset:1024
	ds_read_b128 v[138:141], v80 offset:2048
	ds_read_b128 v[142:145], v80 offset:3072
	v_add_u32_e32 v80, s90, v245
	ds_read_b128 v[146:149], v80
	ds_read_b128 v[150:153], v80 offset:1024
	ds_read_b128 v[154:157], v80 offset:2048
	ds_read_b128 v[158:161], v80 offset:3072
	s_add_u32 s22, s58, s0
	s_addc_u32 s23, s59, 0
	s_mov_b32 m0, s70
	ds_read_b128 v[162:165], v248 offset:32768
	ds_read_b128 v[166:169], v248 offset:33792
	ds_read_b128 v[170:173], v248 offset:34816
	ds_read_b128 v[174:177], v248 offset:35840
	ds_read_b128 v[178:181], v248 offset:36864
	ds_read_b128 v[198:201], v248 offset:37888
	ds_read_b128 v[202:205], v248 offset:38912
	ds_read_b128 v[206:209], v248 offset:39936
	global_load_lds_dwordx4 v184, s[58:59]
	s_mov_b32 m0, s71
	s_nop 0
	global_load_lds_dwordx4 v188, s[58:59]
	s_mov_b32 m0, s72
	s_nop 0
	global_load_lds_dwordx4 v184, s[22:23]
	s_mov_b32 m0, s73
	s_nop 0
	global_load_lds_dwordx4 v188, s[22:23]
	s_waitcnt vmcnt(8)
	s_waitcnt lgkmcnt(0)
	v_mfma_f32_16x16x32_bf16 v[4:7], v[130:133], v[162:165], v[4:7]
	v_mfma_f32_16x16x32_bf16 v[0:3], v[138:141], v[162:165], v[0:3]
	s_barrier
	s_setprio 1
	s_waitcnt lgkmcnt(0)
	v_mfma_f32_16x16x32_bf16 v[20:23], v[130:133], v[170:173], v[20:23]
	v_mfma_f32_16x16x32_bf16 v[16:19], v[138:141], v[170:173], v[16:19]
	v_mfma_f32_16x16x32_bf16 v[36:39], v[130:133], v[178:181], v[36:39]
	v_mfma_f32_16x16x32_bf16 v[32:35], v[138:141], v[178:181], v[32:35]
	v_mfma_f32_16x16x32_bf16 v[52:55], v[130:133], v[202:205], v[52:55]
	v_mfma_f32_16x16x32_bf16 v[48:51], v[138:141], v[202:205], v[48:51]
	v_mfma_f32_16x16x32_bf16 v[4:7], v[134:137], v[166:169], v[4:7]
	v_mfma_f32_16x16x32_bf16 v[0:3], v[142:145], v[166:169], v[0:3]
	v_mfma_f32_16x16x32_bf16 v[20:23], v[134:137], v[174:177], v[20:23]
	v_mfma_f32_16x16x32_bf16 v[16:19], v[142:145], v[174:177], v[16:19]
	v_mfma_f32_16x16x32_bf16 v[36:39], v[134:137], v[198:201], v[36:39]
	v_mfma_f32_16x16x32_bf16 v[32:35], v[142:145], v[198:201], v[32:35]
	v_mfma_f32_16x16x32_bf16 v[52:55], v[134:137], v[206:209], v[52:55]
	v_mfma_f32_16x16x32_bf16 v[48:51], v[142:145], v[206:209], v[48:51]
	s_setprio 0
	s_setprio 1
	v_mfma_f32_16x16x32_bf16 v[12:15], v[146:149], v[162:165], v[12:15]
	v_mfma_f32_16x16x32_bf16 v[8:11], v[154:157], v[162:165], v[8:11]
	v_mfma_f32_16x16x32_bf16 v[28:31], v[146:149], v[170:173], v[28:31]
	v_mfma_f32_16x16x32_bf16 v[24:27], v[154:157], v[170:173], v[24:27]
	v_mfma_f32_16x16x32_bf16 v[44:47], v[146:149], v[178:181], v[44:47]
	v_mfma_f32_16x16x32_bf16 v[40:43], v[154:157], v[178:181], v[40:43]
	v_mfma_f32_16x16x32_bf16 v[60:63], v[146:149], v[202:205], v[60:63]
	v_mfma_f32_16x16x32_bf16 v[56:59], v[154:157], v[202:205], v[56:59]
	v_mfma_f32_16x16x32_bf16 v[12:15], v[150:153], v[166:169], v[12:15]
	v_mfma_f32_16x16x32_bf16 v[8:11], v[158:161], v[166:169], v[8:11]
	v_mfma_f32_16x16x32_bf16 v[28:31], v[150:153], v[174:177], v[28:31]
	v_mfma_f32_16x16x32_bf16 v[24:27], v[158:161], v[174:177], v[24:27]
	v_mfma_f32_16x16x32_bf16 v[44:47], v[150:153], v[198:201], v[44:47]
	v_mfma_f32_16x16x32_bf16 v[40:43], v[158:161], v[198:201], v[40:43]
	v_mfma_f32_16x16x32_bf16 v[60:63], v[150:153], v[206:209], v[60:63]
	v_mfma_f32_16x16x32_bf16 v[56:59], v[158:161], v[206:209], v[56:59]
	s_setprio 0
	s_barrier
; #define PG8_STAGE(bufoff, gbase, voff) do { _Pragma("unroll") for (int _i = 0; _i < 2; ++_i) \
;         __builtin_amdgcn_global_load_lds((const unsigned*)((const char*)(gbase) + (voff)[_i]), (PG8_LAS unsigned*)(lds + (bufoff) + ldsw + _i * 8192), 16, 0, 0); } while (0)
; #define PG8_LDA(dst, b, h) do { _Pragma("unroll") for (int m = 0; m < 4; ++m) _Pragma("unroll") for (int k = 0; k < 2; ++k) dst[m][k] = *(const PG8_LAS bf16x8*)(lds + PG8_SA(b, h) + aoff + m * 2048 + k * 1024); } while (0)
; #define PG8_WAIT_V(n) asm volatile("s_waitcnt vmcnt(" #n ")" ::: "memory")
; template <class Epi, class Sched, bool ALIGN_EPI = false>
; __device__ __forceinline__ void gemm_phase(PG8_LAS unsigned char* lds, const Gemm g, const Sched& S, const Epi& E, int tid_in) {
;     ...
;         for (int t = 0; t < nt; t += 2) {
;             const bool last = (t == nt - 2);
;             const char* a1 = cA + (size_t)(t + 1) * kstep;
;             const char* a2 = last ? nA : cA + (size_t)(t + 2) * kstep; const char* b2 = last ? nB : cB + (size_t)(t + 2) * kstep;
;             const char* a3 = a2 + kstep; const char* b3 = b2 + kstep;
;             if (last && has_next) S.a_ready(nxt);
;             E.mid(acc, cur, t, tid_, wr, wc);
;             PG8_LDB(B0, 0, 0); PG8_LDB(B1, 0, 1); PG8_SCHED; PG8_LDA(At, 0, 0); PG8_STAGE(PG8_SA(1, 1), a1 + hstepA, voffA);
;             PG8_WAIT_V(8); PG8_WAIT_L(0); PG8_BAR; PG8_MMA(0, 0, At, B0); PG8_MMA(0, 1, At, B1); PG8_BAR; PG8_SCHED;
;             PG8_LDA(At, 0, 1); PG8_STAGE(PG8_SB(0, 0), b2, voffB); PG8_STAGE(PG8_SB(0, 1), b2 + hstepB, voffB); PG8_STAGE(PG8_SA(0, 0), a2, voffA);
;             PG8_WAIT_V(8); PG8_WAIT_L(0); PG8_BAR; PG8_MMA(1, 0, At, B0); PG8_MMA(1, 1, At, B1); PG8_BAR; PG8_SCHED;
;             PG8_LDB(B0, 1, 0); PG8_LDB(B1, 1, 1); PG8_SCHED; PG8_LDA(At, 1, 0); PG8_STAGE(PG8_SA(0, 1), a2 + hstepA, voffA);
;             PG8_WAIT_V(8); PG8_WAIT_L(0); PG8_BAR; PG8_MMA(0, 0, At, B0); PG8_MMA(0, 1, At, B1); PG8_BAR; PG8_SCHED;
;             PG8_LDA(At, 1, 1); PG8_STAGE(PG8_SB(1, 0), b3, voffB); PG8_STAGE(PG8_SB(1, 1), b3 + hstepB, voffB); PG8_STAGE(PG8_SA(1, 0), a3, voffA);
;             PG8_WAIT_V(8); PG8_WAIT_L(0); PG8_BAR; PG8_MMA(1, 0, At, B0); PG8_MMA(1, 1, At, B1); PG8_BAR; PG8_SCHED;
;         }
;         if constexpr (ALIGN_EPI) { if (wr == 0) PG8_BAR; }
;         E(acc, cur, wr, wc, fr, fq); S.done(cur);
	s_add_i32 s22, s89, s69
	s_add_u32 vcc_lo, vcc_lo, 0x80
	s_addc_u32 vcc_hi, vcc_hi, 0
	s_mov_b32 m0, s22
	ds_read_b128 v[162:165], v248 offset:49152
	ds_read_b128 v[166:169], v248 offset:50176
	ds_read_b128 v[170:173], v248 offset:51200
	ds_read_b128 v[174:177], v248 offset:52224
	ds_read_b128 v[178:181], v248 offset:53248
	ds_read_b128 v[198:201], v248 offset:54272
	ds_read_b128 v[202:205], v248 offset:55296
	ds_read_b128 v[206:209], v248 offset:56320
	global_load_lds_dwordx4 v186, vcc
	s_add_i32 m0, s22, 0x2000
	s_add_i32 s22, s90, s69
	global_load_lds_dwordx4 v190, vcc
	s_add_u32 vcc_lo, vcc_lo, s33
	s_addc_u32 vcc_hi, vcc_hi, 0
	s_mov_b32 m0, s22
	s_nop 0
	global_load_lds_dwordx4 v186, vcc
	s_add_i32 m0, s22, 0x2000
	s_nop 0
	global_load_lds_dwordx4 v190, vcc
	s_waitcnt vmcnt(6)
	s_waitcnt lgkmcnt(0)
	v_mfma_f32_16x16x32_bf16 v[64:67], v[130:133], v[162:165], v[64:67]
	v_mfma_f32_16x16x32_bf16 v[68:71], v[138:141], v[162:165], v[68:71]
	s_barrier
	s_setprio 1
	s_waitcnt lgkmcnt(0)
	v_mfma_f32_16x16x32_bf16 v[82:85], v[130:133], v[170:173], v[82:85]
	v_mfma_f32_16x16x32_bf16 v[86:89], v[138:141], v[170:173], v[86:89]
	v_mfma_f32_16x16x32_bf16 v[98:101], v[130:133], v[178:181], v[98:101]
	v_mfma_f32_16x16x32_bf16 v[102:105], v[138:141], v[178:181], v[102:105]
	v_mfma_f32_16x16x32_bf16 v[114:117], v[130:133], v[202:205], v[114:117]
	v_mfma_f32_16x16x32_bf16 v[118:121], v[138:141], v[202:205], v[118:121]
	v_mfma_f32_16x16x32_bf16 v[64:67], v[134:137], v[166:169], v[64:67]
	v_mfma_f32_16x16x32_bf16 v[68:71], v[142:145], v[166:169], v[68:71]
	v_mfma_f32_16x16x32_bf16 v[82:85], v[134:137], v[174:177], v[82:85]
	v_mfma_f32_16x16x32_bf16 v[86:89], v[142:145], v[174:177], v[86:89]
	v_mfma_f32_16x16x32_bf16 v[98:101], v[134:137], v[198:201], v[98:101]
	v_mfma_f32_16x16x32_bf16 v[102:105], v[142:145], v[198:201], v[102:105]
	v_mfma_f32_16x16x32_bf16 v[114:117], v[134:137], v[206:209], v[114:117]
	v_mfma_f32_16x16x32_bf16 v[118:121], v[142:145], v[206:209], v[118:121]
	s_setprio 0
	s_setprio 1
	v_mfma_f32_16x16x32_bf16 v[76:79], v[146:149], v[162:165], v[76:79]
	v_mfma_f32_16x16x32_bf16 v[72:75], v[154:157], v[162:165], v[72:75]
	v_mfma_f32_16x16x32_bf16 v[94:97], v[146:149], v[170:173], v[94:97]
	v_mfma_f32_16x16x32_bf16 v[90:93], v[154:157], v[170:173], v[90:93]
	v_mfma_f32_16x16x32_bf16 v[110:113], v[146:149], v[178:181], v[110:113]
	v_mfma_f32_16x16x32_bf16 v[106:109], v[154:157], v[178:181], v[106:109]
	v_mfma_f32_16x16x32_bf16 v[126:129], v[146:149], v[202:205], v[126:129]
	v_mfma_f32_16x16x32_bf16 v[122:125], v[154:157], v[202:205], v[122:125]
	v_mfma_f32_16x16x32_bf16 v[76:79], v[150:153], v[166:169], v[76:79]
	v_mfma_f32_16x16x32_bf16 v[72:75], v[158:161], v[166:169], v[72:75]
	v_mfma_f32_16x16x32_bf16 v[94:97], v[150:153], v[174:177], v[94:97]
	v_mfma_f32_16x16x32_bf16 v[90:93], v[158:161], v[174:177], v[90:93]
	v_mfma_f32_16x16x32_bf16 v[110:113], v[150:153], v[198:201], v[110:113]
	v_mfma_f32_16x16x32_bf16 v[106:109], v[158:161], v[198:201], v[106:109]
	v_mfma_f32_16x16x32_bf16 v[126:129], v[150:153], v[206:209], v[126:129]
	v_mfma_f32_16x16x32_bf16 v[122:125], v[158:161], v[206:209], v[122:125]
	s_setprio 0
	s_add_u32 s60, s60, 0x100
	s_addc_u32 s61, s61, 0
	s_add_u32 s57, s57, 0x100
	s_addc_u32 s62, s62, 0
	s_cmp_ge_u32 s63, s76
	s_mov_b32 s58, s63
	s_cbranch_scc1 .Lk_exitbar
	s_add_i32 s63, s58, 2
	s_add_u32 s22, s60, 0x80
	s_addc_u32 s23, s61, 0
	s_add_i32 s89, 0, 0x10000
	s_cmp_eq_u32 s77, s58
	s_cselect_b32 s59, s19, s23
	s_cselect_b32 s58, s18, s22
	v_add_u32_e32 v80, s89, v245
	s_cselect_b32 s23, s35, s62
	s_cselect_b32 s22, s34, s57
	s_add_i32 s90, 0, 0x14000
	s_barrier
	s_branch .LBB0_267
.Lk_exitbar:
	s_barrier
.Lkloop_exit:
	s_and_b64 vcc, exec, s[14:15]
	s_cbranch_vccnz .LBB0_271
	s_cmp_lt_i32 s64, 3
	s_mov_b64 s[58:59], -1
	s_cbranch_scc0 .LBB0_272
